# attention: LDS reads (V fragments, next tile K fragments) spread over MFMA gaps instead of bursts; K fragments prefetched during PV; K DMA 3 tiles ahead
# speedup vs baseline: 1.0608x; 1.0058x over previous
; #define SBAR() __builtin_amdgcn_sched_barrier(0)
; template<int THRL> __device__ __forceinline__ void attn_unit(int qb,const bf16*Q,const bf16*__restrict__ K,const bf16*__restrict__ V,bf16*O,char*shm){
;     ...
;     float a=MX3(C0[0],C0[1],C1[0]),b=MX3(C0[2],C0[3],C1[1]); a=MX3(a,C1[2],C1[3]);
;     #pragma unroll
;     for(int r=4;r<16;r+=4){a=MX3(a,C0[r],C0[r+1]);b=MX3(b,C0[r+2],C0[r+3]);a=MX3(a,C1[r],C1[r+1]);b=MX3(b,C1[r+2],C1[r+3]);}
;     float rm=__builtin_fmaxf(a,b); { auto rr=__builtin_amdgcn_permlane32_swap(__float_as_uint(rm),__float_as_uint(rm),false,false); rm=__builtin_fmaxf(__uint_as_float(rr[0]),__uint_as_float(rr[1])); }
;     if(t==0 || __any(rm>(float)THRL)){
;       const float dl=(t==0)?rm:__builtin_fmaxf(rm,0.f); mhat+=dl;
;       #pragma unroll
;       for(int r=0;r<16;++r){C0[r]-=dl;C1[r]-=dl;}
;       #pragma unroll
;       for(int r=0;r<16;++r)negm[r]=-mhat;
;       if(t!=0){ const float f=__builtin_amdgcn_exp2f(-dl); l_reg*=f; if(hi==0)wsf[r32]=f; asm volatile("s_waitcnt lgkmcnt(0)":::"memory");
;         #pragma unroll
;         for(int d_=0;d_<4;++d_)
;           #pragma unroll
;           for(int r=0;r<16;++r)o[d_][r]*=wsf[crow(r,hi)]; } }
;     #pragma unroll
;     for(int r=0;r<16;++r){C0[r]=__builtin_amdgcn_exp2f(C0[r]);C1[r]=__builtin_amdgcn_exp2f(C1[r]);}
;     { float s0=C0[0]+C0[1],s1=C1[0]+C1[1];
;       #pragma unroll
;       for(int r=2;r<16;++r){s0+=C0[r];s1+=C1[r];}
;       l_reg+=s0+s1; }
;     const u32x4 pw0=(u32x4){PKW(C0,0),PKW(C0,2),PKW(C0,4),PKW(C0,6)},pw1=(u32x4){PKW(C0,8),PKW(C0,10),PKW(C0,12),PKW(C0,14)},pw2=(u32x4){PKW(C1,0),PKW(C1,2),PKW(C1,4),PKW(C1,6)},pw3=(u32x4){PKW(C1,8),PKW(C1,10),PKW(C1,12),PKW(C1,14)};
;     SBAR();
;     ...
;     s16x4 w2l_[4],w2h_[4],w3l_[4],w3h_[4];
;     #pragma unroll
;     for(int d_=0;d_<4;++d_){ w2l_[d_]=vtr(vp_+(d_*4096+2*1024)); w2h_[d_]=vtr(vp_+(d_*4096+2*1024+512)); }
;     SBAR();
;     #pragma unroll
;     for(int d_=0;d_<4;++d_){ o[d_]=__builtin_amdgcn_mfma_f32_32x32x16_bf16(__builtin_bit_cast(bf16x8,pw0),VFRAG(vl_,vh_,d_*2),o[d_],0,0,0); }
;     SBAR();
;     #pragma unroll
;     for(int d_=0;d_<4;++d_){ w3l_[d_]=vtr(vp_+(d_*4096+3*1024)); w3h_[d_]=vtr(vp_+(d_*4096+3*1024+512)); }
;     SBAR();
;     #pragma unroll
;     for(int d_=0;d_<4;++d_){ o[d_]=__builtin_amdgcn_mfma_f32_32x32x16_bf16(__builtin_bit_cast(bf16x8,pw1),VFRAG(vl_,vh_,d_*2+1),o[d_],0,0,0); }
;     #pragma unroll
.LBB0_363:
	v_max_f32_e32 v40, v1, v1
	v_max_f32_e32 v41, v0, v0
	v_max_f32_e32 v40, v41, v40
	s_nop 6
	v_max3_f32 v41, v2, v3, v17
	v_max3_f32 v40, v40, v16, v18
	v_max3_f32 v40, v40, v19, v4
	v_max3_f32 v41, v41, v6, v7
	v_max3_f32 v40, v40, v5, v20
	v_max3_f32 v41, v41, v22, v23
	v_max3_f32 v40, v40, v21, v8
	v_max3_f32 v41, v41, v10, v11
	v_max3_f32 v40, v40, v9, v24
	v_max3_f32 v41, v41, v26, v27
	v_max3_f32 v40, v40, v25, v12
	v_max3_f32 v41, v41, v14, v15
	v_max3_f32 v40, v40, v13, v28
	v_max3_f32 v41, v41, v30, v31
	v_max3_f32 v40, v40, v29, v41
	v_mov_b32_e32 v41, v40
	s_nop 1
	v_permlane32_swap_b32_e32 v40, v41
	v_max_f32_e32 v41, v41, v41
	v_max_f32_e32 v40, v40, v40
	v_max_f32_e32 v64, v40, v41
	v_sub_f32_e32 v16, v16, v64
	v_sub_f32_e32 v17, v17, v64
	v_sub_f32_e32 v0, v0, v64
	v_sub_f32_e32 v1, v1, v64
	v_sub_f32_e32 v18, v18, v64
	v_sub_f32_e32 v40, v27, v64
	v_sub_f32_e32 v41, v29, v64
	v_sub_f32_e32 v42, v30, v64
	v_sub_f32_e32 v44, v31, v64
	v_sub_f32_e32 v2, v2, v64
	v_sub_f32_e32 v27, v4, v64
	v_sub_f32_e32 v29, v5, v64
	v_sub_f32_e32 v30, v6, v64
	v_sub_f32_e32 v31, v7, v64
	v_exp_f32_e32 v5, v0
	v_exp_f32_e32 v4, v16
	v_exp_f32_e32 v7, v1
	v_exp_f32_e32 v6, v17
	v_sub_f32_e32 v19, v19, v64
	v_sub_f32_e32 v3, v3, v64
	v_sub_f32_e32 v43, v8, v64
	v_sub_f32_e32 v45, v9, v64
	v_exp_f32_e32 v9, v2
	v_exp_f32_e32 v8, v18
	v_sub_f32_e32 v20, v20, v64
	v_sub_f32_e32 v46, v10, v64
	v_sub_f32_e32 v47, v11, v64
	v_exp_f32_e32 v11, v3
	v_exp_f32_e32 v10, v19
	v_sub_f32_e32 v21, v21, v64
	v_sub_f32_e32 v48, v12, v64
	v_sub_f32_e32 v49, v13, v64
	v_exp_f32_e32 v13, v27
	v_exp_f32_e32 v12, v20
	v_sub_f32_e32 v22, v22, v64
	v_sub_f32_e32 v50, v14, v64
	v_sub_f32_e32 v51, v15, v64
	v_exp_f32_e32 v15, v29
	v_exp_f32_e32 v14, v21
	v_pk_add_f32 v[0:1], v[4:5], v[6:7]
	v_sub_f32_e32 v23, v23, v64
	v_exp_f32_e32 v17, v30
	v_exp_f32_e32 v16, v22
	v_pk_add_f32 v[0:1], v[8:9], v[0:1]
	v_sub_f32_e32 v24, v24, v64
	v_exp_f32_e32 v19, v31
	v_exp_f32_e32 v18, v23
	v_pk_add_f32 v[0:1], v[10:11], v[0:1]
	v_sub_f32_e32 v25, v25, v64
	v_exp_f32_e32 v21, v43
	v_exp_f32_e32 v20, v24
	v_pk_add_f32 v[0:1], v[12:13], v[0:1]
	v_sub_f32_e32 v26, v26, v64
	v_exp_f32_e32 v23, v45
	v_exp_f32_e32 v22, v25
	v_pk_add_f32 v[0:1], v[14:15], v[0:1]
	v_exp_f32_e32 v25, v46
	v_exp_f32_e32 v24, v26
	v_pk_add_f32 v[0:1], v[16:17], v[0:1]
	v_sub_f32_e32 v28, v28, v64
	v_exp_f32_e32 v27, v47
	v_exp_f32_e32 v26, v40
	v_pk_add_f32 v[0:1], v[18:19], v[0:1]
	v_exp_f32_e32 v29, v48
	v_exp_f32_e32 v28, v28
	v_pk_add_f32 v[0:1], v[20:21], v[0:1]
	v_exp_f32_e32 v31, v49
	v_exp_f32_e32 v30, v41
	v_pk_add_f32 v[0:1], v[22:23], v[0:1]
	v_exp_f32_e32 v41, v50
	v_exp_f32_e32 v40, v42
	v_pk_add_f32 v[0:1], v[24:25], v[0:1]
	v_exp_f32_e32 v43, v51
	v_exp_f32_e32 v42, v44
	v_pk_add_f32 v[0:1], v[26:27], v[0:1]
	v_cmp_gt_u32_e64 s[4:5], 32, v186
	v_pk_add_f32 v[0:1], v[28:29], v[0:1]
	s_mov_b32 s27, 2
	v_pk_add_f32 v[0:1], v[30:31], v[0:1]
	v_lshl_add_u32 v191, v177, 2, s25
	v_pk_add_f32 v[0:1], v[40:41], v[0:1]
	v_cvt_pk_bf16_f32 v2, v13, v15
	v_pk_add_f32 v[0:1], v[42:43], v[0:1]
	v_cvt_pk_bf16_f32 v3, v17, v19
	v_pk_add_f32 v[110:111], v[0:1], v[0:1] op_sel_hi:[0,1]
	v_cvt_pk_bf16_f32 v0, v5, v7
	v_cvt_pk_bf16_f32 v1, v9, v11
	v_lshlrev_b32_e32 v148, 4, v175
	v_cvt_pk_bf16_f32 v94, v21, v23
	v_cvt_pk_bf16_f32 v95, v25, v27
	v_cvt_pk_bf16_f32 v96, v29, v31
	v_cvt_pk_bf16_f32 v97, v41, v43
	v_cvt_pk_bf16_f32 v98, v4, v6
	v_cvt_pk_bf16_f32 v99, v8, v10
	v_cvt_pk_bf16_f32 v100, v12, v14
	v_cvt_pk_bf16_f32 v101, v16, v18
	v_cvt_pk_bf16_f32 v102, v20, v22
	v_cvt_pk_bf16_f32 v103, v24, v26
	v_cvt_pk_bf16_f32 v104, v28, v30
	v_cvt_pk_bf16_f32 v105, v40, v42
	ds_read_b64_tr_b16 v[106:107], v190 offset:26624
	ds_read_b64_tr_b16 v[108:109], v190 offset:27136
	ds_read_b64_tr_b16 v[128:129], v190 offset:30720
	ds_read_b64_tr_b16 v[130:131], v190 offset:31232
	ds_read_b64_tr_b16 v[132:133], v190 offset:34816
	ds_read_b64_tr_b16 v[134:135], v190 offset:35328
	ds_read_b64_tr_b16 v[136:137], v190 offset:38912
	ds_read_b64_tr_b16 v[138:139], v190 offset:39424
	v_mfma_f32_32x32x16_bf16 v[48:63], v[0:3], v[36:39], 0
	v_mov_b32_e32 v65, v111
	v_add_f32_e64 v178, v64, 0
	v_add_f32_e64 v179, v65, 0
	v_add_f32_e64 v64, -v178, neg(0)
	v_add_f32_e64 v65, -v179, neg(0)
	s_waitcnt lgkmcnt(14)
	v_mfma_f32_32x32x16_bf16 v[32:47], v[0:3], v[32:35], 0
	v_mfma_f32_32x32x16_bf16 v[16:31], v[0:3], v[82:85], 0
	s_waitcnt lgkmcnt(10)
	v_mfma_f32_32x32x16_bf16 v[0:15], v[0:3], v[86:89], 0
	ds_read_b64_tr_b16 v[82:83], v190 offset:27648
	ds_read_b64_tr_b16 v[84:85], v190 offset:28160
	ds_read_b64_tr_b16 v[86:87], v190 offset:31744
	ds_read_b64_tr_b16 v[88:89], v190 offset:32256
	ds_read_b64_tr_b16 v[140:141], v190 offset:35840
	ds_read_b64_tr_b16 v[142:143], v190 offset:36352
	ds_read_b64_tr_b16 v[144:145], v190 offset:39936
	ds_read_b64_tr_b16 v[146:147], v190 offset:40448
	v_mfma_f32_32x32x16_bf16 v[48:63], v[94:97], v[78:81], v[48:63]
	v_mfma_f32_32x32x16_bf16 v[32:47], v[94:97], v[74:77], v[32:47]
	v_mfma_f32_32x32x16_bf16 v[16:31], v[94:97], v[70:73], v[16:31]
	s_waitcnt lgkmcnt(14)
	v_mfma_f32_32x32x16_bf16 v[0:15], v[94:97], v[66:69], v[0:15]
	v_mfma_f32_32x32x16_bf16 v[48:63], v[98:101], v[106:109], v[48:63]
	s_waitcnt lgkmcnt(12)
	v_mfma_f32_32x32x16_bf16 v[32:47], v[98:101], v[128:131], v[32:47]
	s_waitcnt lgkmcnt(10)
	v_mfma_f32_32x32x16_bf16 v[16:31], v[98:101], v[132:135], v[16:31]
	s_waitcnt lgkmcnt(8)
	v_mfma_f32_32x32x16_bf16 v[0:15], v[98:101], v[136:139], v[0:15]
	s_waitcnt lgkmcnt(6)
	v_mfma_f32_32x32x16_bf16 v[48:63], v[102:105], v[82:85], v[48:63]
	s_waitcnt lgkmcnt(4)
	v_mfma_f32_32x32x16_bf16 v[32:47], v[102:105], v[86:89], v[32:47]
	s_waitcnt lgkmcnt(2)
	v_mfma_f32_32x32x16_bf16 v[16:31], v[102:105], v[140:143], v[16:31]
	s_waitcnt lgkmcnt(0)
	v_mfma_f32_32x32x16_bf16 v[0:15], v[102:105], v[144:147], v[0:15]
	ds_read_b128 v[236:239], v189 offset:8192
	ds_read_b128 v[128:131], v189 offset:8704
	ds_read_b128 v[240:243], v189 offset:10240
	ds_read_b128 v[132:135], v189 offset:10752
	ds_read_b128 v[244:247], v189 offset:12288
	ds_read_b128 v[144:147], v189 offset:12800
	ds_read_b128 v[248:251], v189 offset:14336
	ds_read_b128 v[194:197], v189 offset:14848
	s_lshl_b32 s31, s26, 6
	s_sub_i32 s28, 0, s26
	v_subrev_u32_e32 v65, s31, v93
	s_lshl_b64 s[14:15], s[14:15], 1
	v_add_u32_e32 v192, 0x17b, v65
	v_and_b32_e32 v65, 3, v92
	s_add_u32 s12, s14, s12
	v_lshlrev_b32_e32 v66, 4, v65
	v_mov_b32_e32 v67, v161
	s_addc_u32 s13, s15, s13
	s_waitcnt vmcnt(2) lgkmcnt(0)
	s_barrier
; #define SBAR() __builtin_amdgcn_sched_barrier(0)
; #define WAIT_BAR(N) asm volatile("s_waitcnt vmcnt(" #N ") lgkmcnt(0)\n\ts_barrier":::"memory")
; __device__ __forceinline__ s16x4 vtr(lds_cptr p){ return __builtin_bit_cast(s16x4,__builtin_amdgcn_ds_read_tr16_b64_v4i16((__attribute__((address_space(3))) v4i16_t*)p)); }
;   #define DMA_K(t,s3) glds16(ksrc+(long)(t)*KVBLK*DM,(unsigned)__builtin_amdgcn_readfirstlane(kdst+(s3)*SLOTB))
; template<int THRL> __device__ __forceinline__ void attn_unit(int qb,const bf16*Q,const bf16*__restrict__ K,const bf16*__restrict__ V,bf16*O,char*shm){
;     ...
;   DMA_K(0,0);DMA_V(0,0);DMA_K(1,1);DMA_V(1,1);
;   int c0=0,c1=1,c2=2;
;     ...
;   const bf16*Qw=Q+(long)(q0+wid*QBLK)*DM;
;   bf16x8 qr[4];
;   #pragma unroll
;   for(int d0=0;d0<4;++d0)qr[d0]=*reinterpret_cast<const bf16x8*>(&Qw[(long)r32*DM+d0*16+hi*8]);
;   float mhat=0.f,l_reg=0.f; f32x16 negm=f32x16{};
;   f32x16 o[4]; o[0]=f32x16{};o[1]=f32x16{};o[2]=f32x16{};o[3]=f32x16{};
;   const int qrel=wid*QBLK+r32;
;   const lds_cptr kp0=shm3+LDS_K+hi*1024+r32*16;
;   const lds_cptr vp0=shm3+LDS_V+((lane>>4)&1)*32+(lane&3)*8+(4*hi+((lane&15)>>2))*64;
;   WAIT_BAR(3);
;   for(int t=0;t<NT;++t){
;     if(t+2<NT){DMA_K(t+2,c2);DMA_V(t+2,c2);}
;     bf16x8 kf[8]; kload8(kf,kp0+c0*SLOTB);
;     SBAR();
;     f32x16 C0,C1;
;     {
;       C0=__builtin_amdgcn_mfma_f32_32x32x16_bf16(kf[0],qr[0],negm,0,0,0); C1=__builtin_amdgcn_mfma_f32_32x32x16_bf16(kf[1],qr[0],negm,0,0,0);
;       C0=__builtin_amdgcn_mfma_f32_32x32x16_bf16(kf[2],qr[1],C0,0,0,0);   C1=__builtin_amdgcn_mfma_f32_32x32x16_bf16(kf[3],qr[1],C1,0,0,0);
;       C0=__builtin_amdgcn_mfma_f32_32x32x16_bf16(kf[4],qr[2],C0,0,0,0);   C1=__builtin_amdgcn_mfma_f32_32x32x16_bf16(kf[5],qr[2],C1,0,0,0);
;       C0=__builtin_amdgcn_mfma_f32_32x32x16_bf16(kf[6],qr[3],C0,0,0,0);   C1=__builtin_amdgcn_mfma_f32_32x32x16_bf16(kf[7],qr[3],C1,0,0,0); }
;     SBAR();
;     const lds_cptr vp_=vp0+c0*VSLOTB; s16x4 vl_[8],vh_[8];
;     #pragma unroll
;     for(int k2=0;k2<2;++k2)
;       #pragma unroll
;       for(int d_=0;d_<4;++d_){ vl_[d_*2+k2]=vtr(vp_+(d_*4096+k2*1024)); vh_[d_*2+k2]=vtr(vp_+(d_*4096+k2*1024+512)); }
;     SBAR();
;     { const int jb_=t-(NT-4); if(jb_>=0)cmask(C0,C1,jb_,qrel,hi); }
	v_lshl_add_u64 v[66:67], s[12:13], 0, v[66:67]
	v_lshl_add_u64 v[66:67], v[66:67], 0, v[160:161]
	s_mov_b64 s[12:13], 0xc6000
	s_mov_b32 s29, 0
	s_mov_b32 s35, 1
	v_lshl_add_u64 v[180:181], s[6:7], 0, v[66:67]
	v_lshl_add_u64 v[182:183], v[90:91], 0, s[12:13]
	s_mov_b32 m0, s9
	s_nop 0
	global_load_lds_dwordx4 v[182:183], off
	v_lshl_add_u64 v[182:183], v[182:183], 0, s[88:89]
	v_add_u32_e32 v160, s25, v148
	s_mov_b32 s31, 1
	v_mov_b32_e32 v65, v64
	v_mov_b32_e32 v66, v64
	v_mov_b32_e32 v67, v64
	v_mov_b32_e32 v68, v64
	v_mov_b32_e32 v69, v64
	v_mov_b32_e32 v70, v64
	v_mov_b32_e32 v71, v64
	v_mov_b32_e32 v72, v64
	v_mov_b32_e32 v73, v64
	v_mov_b32_e32 v74, v64
	v_mov_b32_e32 v75, v64
	v_mov_b32_e32 v76, v64
	v_mov_b32_e32 v77, v64
	v_mov_b32_e32 v78, v64
	v_mov_b32_e32 v79, v64
.LBB0_364:
	s_add_i32 s12, s31, 3
	s_cmp_ge_i32 s12, s26
	s_cselect_b64 s[12:13], -1, 0
	s_mov_b32 s34, s35
	s_and_b64 vcc, exec, s[12:13]
.LBB0_366:
.Lattn_top:
	s_lshl_b32 s14, s34, 14
	v_add_u32_e32 v193, s14, v190
	v_mfma_f32_32x32x16_bf16 v[80:95], v[236:239], v[112:115], v[64:79]
	ds_read_b64_tr_b16 v[156:157], v193 offset:24576
	ds_read_b64_tr_b16 v[158:159], v193 offset:25088
	v_mfma_f32_32x32x16_bf16 v[80:95], v[240:243], v[116:119], v[80:95]
	ds_read_b64_tr_b16 v[140:141], v193 offset:25600
	ds_read_b64_tr_b16 v[142:143], v193 offset:26112
	v_mfma_f32_32x32x16_bf16 v[80:95], v[244:247], v[120:123], v[80:95]
	ds_read_b64_tr_b16 v[152:153], v193 offset:28672
	ds_read_b64_tr_b16 v[154:155], v193 offset:29184
	v_mfma_f32_32x32x16_bf16 v[80:95], v[248:251], v[124:127], v[80:95]
	ds_read_b64_tr_b16 v[136:137], v193 offset:29696
	ds_read_b64_tr_b16 v[138:139], v193 offset:30208
	v_mfma_f32_32x32x16_bf16 v[96:111], v[128:131], v[112:115], v[64:79]
	ds_read_b64_tr_b16 v[148:149], v193 offset:32768
	ds_read_b64_tr_b16 v[150:151], v193 offset:33280
	v_mfma_f32_32x32x16_bf16 v[96:111], v[132:135], v[116:119], v[96:111]
	ds_read_b64_tr_b16 v[132:133], v193 offset:33792
	ds_read_b64_tr_b16 v[134:135], v193 offset:34304
	v_mfma_f32_32x32x16_bf16 v[96:111], v[144:147], v[120:123], v[96:111]
	ds_read_b64_tr_b16 v[144:145], v193 offset:36864
	ds_read_b64_tr_b16 v[146:147], v193 offset:37376
	v_mfma_f32_32x32x16_bf16 v[96:111], v[194:197], v[124:127], v[96:111]
	ds_read_b64_tr_b16 v[128:129], v193 offset:37888
	ds_read_b64_tr_b16 v[130:131], v193 offset:38400
	s_add_i32 s14, s28, s31
	s_cmp_lt_i32 s14, -4
	s_cbranch_scc1 .LBB0_368
	v_subrev_u32_e32 v163, 27, v192
	v_subrev_u32_e32 v162, 59, v192
	v_cmp_le_i32_e32 vcc, v163, v188
	s_nop 5
	v_cndmask_b32_e32 v96, v229, v96, vcc
	v_cmp_lt_i32_e32 vcc, v162, v188
	s_nop 1
	v_cndmask_b32_e32 v81, v229, v81, vcc
	v_cmp_le_i32_e32 vcc, v162, v188
	v_subrev_u32_e32 v162, 26, v192
	s_nop 0
	v_cndmask_b32_e32 v80, v229, v80, vcc
	v_cmp_le_i32_e32 vcc, v162, v188
	v_subrev_u32_e32 v162, 57, v192
	s_nop 0
	v_cndmask_b32_e32 v97, v229, v97, vcc
	v_cmp_le_i32_e32 vcc, v162, v188
	v_subrev_u32_e32 v162, 25, v192
	s_nop 0
	v_cndmask_b32_e32 v82, v229, v82, vcc
	v_cmp_le_i32_e32 vcc, v162, v188
	v_subrev_u32_e32 v162, 56, v192
	s_nop 0
	v_cndmask_b32_e32 v98, v229, v98, vcc
	v_cmp_le_i32_e32 vcc, v162, v188
	v_subrev_u32_e32 v162, 24, v192
	s_nop 0
	v_cndmask_b32_e32 v83, v229, v83, vcc
	v_cmp_le_i32_e32 vcc, v162, v188
	v_subrev_u32_e32 v162, 51, v192
	s_nop 0
	v_cndmask_b32_e32 v99, v229, v99, vcc
	v_cmp_le_i32_e32 vcc, v162, v188
	v_subrev_u32_e32 v162, 19, v192
	s_nop 0
	v_cndmask_b32_e32 v84, v229, v84, vcc
	v_cmp_le_i32_e32 vcc, v162, v188
	v_subrev_u32_e32 v162, 50, v192
	s_nop 0
	v_cndmask_b32_e32 v100, v229, v100, vcc
	v_cmp_le_i32_e32 vcc, v162, v188
	v_subrev_u32_e32 v162, 18, v192
	s_nop 0
	v_cndmask_b32_e32 v85, v229, v85, vcc
	v_cmp_le_i32_e32 vcc, v162, v188
	v_subrev_u32_e32 v162, 49, v192
	s_nop 0
	v_cndmask_b32_e32 v101, v229, v101, vcc
	v_cmp_le_i32_e32 vcc, v162, v188
	v_subrev_u32_e32 v162, 17, v192
	s_nop 0
	v_cndmask_b32_e32 v86, v229, v86, vcc
	v_cmp_le_i32_e32 vcc, v162, v188
	v_subrev_u32_e32 v162, 48, v192
	s_nop 0
	v_cndmask_b32_e32 v102, v229, v102, vcc
	v_cmp_le_i32_e32 vcc, v162, v188
	v_add_u32_e32 v162, -16, v192
	s_nop 0
	v_cndmask_b32_e32 v87, v229, v87, vcc
	v_cmp_le_i32_e32 vcc, v162, v188
	v_subrev_u32_e32 v162, 43, v192
	s_nop 0
	v_cndmask_b32_e32 v103, v229, v103, vcc
	v_cmp_le_i32_e32 vcc, v162, v188
	v_add_u32_e32 v162, -11, v192
	s_nop 0
	v_cndmask_b32_e32 v88, v229, v88, vcc
	v_cmp_le_i32_e32 vcc, v162, v188
	v_subrev_u32_e32 v162, 42, v192
	s_nop 0
	v_cndmask_b32_e32 v104, v229, v104, vcc
	v_cmp_le_i32_e32 vcc, v162, v188
	v_add_u32_e32 v162, -10, v192
	s_nop 0
	v_cndmask_b32_e32 v89, v229, v89, vcc
	v_cmp_le_i32_e32 vcc, v162, v188
	v_subrev_u32_e32 v162, 41, v192
	s_nop 0
	v_cndmask_b32_e32 v105, v229, v105, vcc
	v_cmp_le_i32_e32 vcc, v162, v188
	v_add_u32_e32 v162, -9, v192
	s_nop 0
	v_cndmask_b32_e32 v90, v229, v90, vcc
	v_cmp_le_i32_e32 vcc, v162, v188
	v_subrev_u32_e32 v162, 40, v192
	s_nop 0
	v_cndmask_b32_e32 v106, v229, v106, vcc
	v_cmp_le_i32_e32 vcc, v162, v188
	v_add_u32_e32 v162, -8, v192
	s_nop 0
	v_cndmask_b32_e32 v91, v229, v91, vcc
	v_cmp_le_i32_e32 vcc, v162, v188
	v_subrev_u32_e32 v162, 35, v192
	s_nop 0
	v_cndmask_b32_e32 v107, v229, v107, vcc
	v_cmp_le_i32_e32 vcc, v162, v188
	v_add_u32_e32 v162, -3, v192
	s_nop 0
	v_cndmask_b32_e32 v92, v229, v92, vcc
	v_cmp_le_i32_e32 vcc, v162, v188
	v_subrev_u32_e32 v162, 34, v192
	s_nop 0
	v_cndmask_b32_e32 v108, v229, v108, vcc
	v_cmp_le_i32_e32 vcc, v162, v188
	v_add_u32_e32 v162, -2, v192
	s_nop 0
	v_cndmask_b32_e32 v93, v229, v93, vcc
	v_cmp_le_i32_e32 vcc, v162, v188
	v_subrev_u32_e32 v162, 33, v192
	s_nop 0
	v_cndmask_b32_e32 v109, v229, v109, vcc
	v_cmp_le_i32_e32 vcc, v162, v188
	v_add_u32_e32 v162, -1, v192
	s_nop 0
	v_cndmask_b32_e32 v94, v229, v94, vcc
	v_cmp_le_i32_e32 vcc, v162, v188
	v_subrev_u32_e32 v162, 32, v192
	s_nop 0
	v_cndmask_b32_e32 v110, v229, v110, vcc
	v_cmp_le_i32_e32 vcc, v162, v188
	s_nop 1
	v_cndmask_b32_e32 v95, v229, v95, vcc
	v_cmp_le_i32_e32 vcc, v192, v188
	s_nop 1
	v_cndmask_b32_e32 v111, v229, v111, vcc

; #define SBAR() __builtin_amdgcn_sched_barrier(0)
; #define WAIT_BAR(N) asm volatile("s_waitcnt vmcnt(" #N ") lgkmcnt(0)\n\ts_barrier":::"memory")
; __device__ __forceinline__ s16x4 vtr(lds_cptr p){ return __builtin_bit_cast(s16x4,__builtin_amdgcn_ds_read_tr16_b64_v4i16((__attribute__((address_space(3))) v4i16_t*)p)); }
;   #define DMA_K(t,s3) glds16(ksrc+(long)(t)*KVBLK*DM,(unsigned)__builtin_amdgcn_readfirstlane(kdst+(s3)*SLOTB))
;   #define DMA_V(t,s3) do{ const unsigned vd_=(unsigned)__builtin_amdgcn_readfirstlane(vdst+(s3)*VSLOTB); glds16(vsrc+(long)(t)*KVBLK*DM,vd_); glds16(vsrc+(long)(t)*KVBLK*DM+64,(unsigned)__builtin_amdgcn_readfirstlane(vd_+8192)); }while(0)
;   #define ROT3() do{ const int x_=c0; c0=c1; c1=c2; c2=x_; }while(0)
; template<int THRL> __device__ __forceinline__ void attn_unit(int qb,const bf16*Q,const bf16*__restrict__ K,const bf16*__restrict__ V,bf16*O,char*shm){
;     ...
;     if(t+2<NT){DMA_K(t+2,c2);DMA_V(t+2,c2);}
;     bf16x8 kf[8]; kload8(kf,kp0+c0*SLOTB);
;     ...
;     for(int d_=0;d_<4;++d_){ w2l_[d_]=vtr(vp_+(d_*4096+2*1024)); w2h_[d_]=vtr(vp_+(d_*4096+2*1024+512)); }
;     SBAR();
;     #pragma unroll
;     for(int d_=0;d_<4;++d_){ o[d_]=__builtin_amdgcn_mfma_f32_32x32x16_bf16(__builtin_bit_cast(bf16x8,pw0),VFRAG(vl_,vh_,d_*2),o[d_],0,0,0); }
;     SBAR();
;     #pragma unroll
;     for(int d_=0;d_<4;++d_){ w3l_[d_]=vtr(vp_+(d_*4096+3*1024)); w3h_[d_]=vtr(vp_+(d_*4096+3*1024+512)); }
;     SBAR();
;     #pragma unroll
;     for(int d_=0;d_<4;++d_){ o[d_]=__builtin_amdgcn_mfma_f32_32x32x16_bf16(__builtin_bit_cast(bf16x8,pw1),VFRAG(vl_,vh_,d_*2+1),o[d_],0,0,0); }
;     #pragma unroll
;     for(int d_=0;d_<4;++d_){ o[d_]=__builtin_amdgcn_mfma_f32_32x32x16_bf16(__builtin_bit_cast(bf16x8,pw2),VFRAG(w2l_,w2h_,d_),o[d_],0,0,0); }
;     #pragma unroll
;     for(int d_=0;d_<4;++d_){ o[d_]=__builtin_amdgcn_mfma_f32_32x32x16_bf16(__builtin_bit_cast(bf16x8,pw3),VFRAG(w3l_,w3h_,d_),o[d_],0,0,0); }
;     SBAR();
;     ...
;     if(t+2<NT){WAIT_BAR(3);}else{WAIT_BAR(0);}
;     ROT3();
.LBB0_372:
	v_exp_f32_e32 v80, v80
	v_exp_f32_e32 v81, v81
	v_exp_f32_e32 v82, v82
	v_exp_f32_e32 v83, v83
	v_exp_f32_e32 v84, v84
	v_exp_f32_e32 v85, v85
	v_exp_f32_e32 v86, v86
	v_exp_f32_e32 v87, v87
	ds_read_b64_tr_b16 v[210:211], v193 offset:26624
	ds_read_b64_tr_b16 v[212:213], v193 offset:27136
	v_cvt_pk_bf16_f32 v194, v80, v81
	v_cvt_pk_bf16_f32 v195, v82, v83
	v_cvt_pk_bf16_f32 v196, v84, v85
	v_cvt_pk_bf16_f32 v197, v86, v87
	s_and_b64 vcc, exec, s[12:13]
	v_exp_f32_e32 v88, v88
	v_exp_f32_e32 v89, v89
	s_waitcnt lgkmcnt(15)
	v_mfma_f32_32x32x16_bf16 v[48:63], v[194:197], v[156:159], v[48:63]
	ds_read_b64_tr_b16 v[214:215], v193 offset:30720
	ds_read_b64_tr_b16 v[216:217], v193 offset:31232
	v_exp_f32_e32 v90, v90
	v_exp_f32_e32 v91, v91
	v_cvt_pk_bf16_f32 v198, v88, v89
	s_waitcnt lgkmcnt(14)
	v_mfma_f32_32x32x16_bf16 v[32:47], v[194:197], v[152:155], v[32:47]
	ds_read_b64_tr_b16 v[218:219], v193 offset:34816
	ds_read_b64_tr_b16 v[220:221], v193 offset:35328
	v_exp_f32_e32 v92, v92
	v_exp_f32_e32 v93, v93
	v_cvt_pk_bf16_f32 v199, v90, v91
	s_cbranch_vccnz .Lattn_nodma0
	s_lshl_b32 s14, s34, 13
	s_add_i32 s14, s14, s9
	s_mov_b32 m0, s14
	s_nop 0
	global_load_lds_dwordx4 v[182:183], off
.Lattn_nodma0:
	s_waitcnt lgkmcnt(12)
	v_mfma_f32_32x32x16_bf16 v[16:31], v[194:197], v[148:151], v[16:31]
	ds_read_b64_tr_b16 v[232:233], v193 offset:38912
	ds_read_b64_tr_b16 v[234:235], v193 offset:39424
	v_exp_f32_e32 v94, v94
	v_exp_f32_e32 v95, v95
	v_cvt_pk_bf16_f32 v200, v92, v93
	v_lshl_add_u32 v164, s27, 13, v189
	s_waitcnt lgkmcnt(10)
	v_mfma_f32_32x32x16_bf16 v[0:15], v[194:197], v[144:147], v[0:15]
	ds_read_b64_tr_b16 v[156:157], v193 offset:39936
	ds_read_b64_tr_b16 v[158:159], v193 offset:40448
	v_cvt_pk_bf16_f32 v201, v94, v95
	v_exp_f32_e32 v96, v96
	v_exp_f32_e32 v97, v97
	v_mfma_f32_32x32x16_bf16 v[48:63], v[198:201], v[140:143], v[48:63]
	ds_read_b64_tr_b16 v[152:153], v193 offset:35840
	ds_read_b64_tr_b16 v[154:155], v193 offset:36352
	v_exp_f32_e32 v98, v98
	v_exp_f32_e32 v99, v99
	v_cvt_pk_bf16_f32 v202, v96, v97
	v_add_f32_e32 v80, v80, v81
	v_mfma_f32_32x32x16_bf16 v[32:47], v[198:201], v[136:139], v[32:47]
	ds_read_b64_tr_b16 v[148:149], v193 offset:31744
	ds_read_b64_tr_b16 v[150:151], v193 offset:32256
	v_exp_f32_e32 v100, v100
	v_exp_f32_e32 v101, v101
	v_cvt_pk_bf16_f32 v203, v98, v99
	v_add_f32_e32 v80, v82, v80
	s_add_i32 s14, s31, 2
	s_cmp_ge_i32 s14, s26
	s_cbranch_scc1 .Lattn_nodma1
	s_lshl_b32 s14, s29, 14
	s_add_i32 s14, s14, s11
	s_mov_b32 m0, s14
	v_lshl_add_u64 v[162:163], v[180:181], 0, s[50:51]
	global_load_lds_dwordx4 v[180:181], off
.Lattn_nodma1:
	v_mfma_f32_32x32x16_bf16 v[16:31], v[198:201], v[132:135], v[16:31]
	ds_read_b64_tr_b16 v[144:145], v193 offset:27648
	ds_read_b64_tr_b16 v[146:147], v193 offset:28160
	v_exp_f32_e32 v102, v102
	v_exp_f32_e32 v103, v103
	v_cvt_pk_bf16_f32 v204, v100, v101
	v_add_f32_e32 v80, v83, v80
	s_waitcnt lgkmcnt(15)
	v_mfma_f32_32x32x16_bf16 v[0:15], v[198:201], v[128:131], v[0:15]
	ds_read_b128 v[236:239], v164
	v_cvt_pk_bf16_f32 v205, v102, v103
	v_exp_f32_e32 v104, v104
	v_exp_f32_e32 v105, v105
	v_add_f32_e32 v80, v84, v80
	s_waitcnt lgkmcnt(15)
	v_mfma_f32_32x32x16_bf16 v[48:63], v[202:205], v[210:213], v[48:63]
	ds_read_b128 v[240:243], v164 offset:2048
	v_exp_f32_e32 v106, v106
	v_exp_f32_e32 v107, v107
	v_cvt_pk_bf16_f32 v206, v104, v105
	v_add_f32_e32 v80, v85, v80
	s_waitcnt lgkmcnt(14)
	v_mfma_f32_32x32x16_bf16 v[32:47], v[202:205], v[214:217], v[32:47]
	s_add_i32 s14, s31, 2
	s_cmp_ge_i32 s14, s26
	s_cbranch_scc1 .Lattn_nodma2
	s_lshl_b32 s14, s29, 14
	s_add_i32 s14, s14, s11
	s_addk_i32 s14, 0x2000
	s_mov_b32 m0, s14
	s_nop 0
	global_load_lds_dwordx4 v[162:163], off
.Lattn_nodma2:
	ds_read_b128 v[244:247], v164 offset:4096
	v_exp_f32_e32 v108, v108
	v_exp_f32_e32 v109, v109
	v_cvt_pk_bf16_f32 v207, v106, v107
	v_add_f32_e32 v80, v86, v80
	s_waitcnt lgkmcnt(13)
	v_mfma_f32_32x32x16_bf16 v[16:31], v[202:205], v[218:221], v[16:31]
	ds_read_b128 v[248:251], v164 offset:6144
	v_exp_f32_e32 v110, v110
	v_exp_f32_e32 v111, v111
	v_cvt_pk_bf16_f32 v208, v108, v109
	v_add_f32_e32 v80, v87, v80
	s_waitcnt lgkmcnt(12)
	v_mfma_f32_32x32x16_bf16 v[0:15], v[202:205], v[232:235], v[0:15]
	ds_read_b128 v[194:197], v164 offset:6656
	v_cvt_pk_bf16_f32 v209, v110, v111
	v_add_f32_e32 v81, v96, v97
	v_add_f32_e32 v80, v88, v80
	v_add_f32_e32 v81, v98, v81
	v_add_u32_e32 v192, 64, v192
	v_lshl_add_u64 v[180:181], v[180:181], 0, s[88:89]
	v_lshl_add_u64 v[182:183], v[182:183], 0, s[88:89]
	s_waitcnt lgkmcnt(5)
	v_mfma_f32_32x32x16_bf16 v[48:63], v[206:209], v[144:147], v[48:63]
	ds_read_b128 v[144:147], v164 offset:4608
	v_add_f32_e32 v80, v89, v80
	v_add_f32_e32 v81, v99, v81
	v_add_f32_e32 v80, v90, v80
	v_add_f32_e32 v81, v100, v81
	v_add_f32_e32 v80, v91, v80
	v_add_f32_e32 v81, v101, v81
	v_mfma_f32_32x32x16_bf16 v[32:47], v[206:209], v[148:151], v[32:47]
	ds_read_b128 v[132:135], v164 offset:2560
	v_add_f32_e32 v80, v92, v80
	v_add_f32_e32 v81, v102, v81
	v_add_f32_e32 v80, v93, v80
	v_add_f32_e32 v81, v103, v81
	v_add_f32_e32 v80, v94, v80
	v_add_f32_e32 v81, v104, v81
	v_mfma_f32_32x32x16_bf16 v[16:31], v[206:209], v[152:155], v[16:31]
	ds_read_b128 v[128:131], v164 offset:512
	v_add_f32_e32 v80, v95, v80
	v_add_f32_e32 v81, v105, v81
	v_add_f32_e32 v81, v106, v81
	v_add_f32_e32 v81, v107, v81
	v_add_f32_e32 v81, v108, v81
	v_add_f32_e32 v81, v109, v81
	v_mfma_f32_32x32x16_bf16 v[0:15], v[206:209], v[156:159], v[0:15]
	v_add_f32_e32 v81, v110, v81
	v_add_f32_e32 v81, v111, v81
	v_add_f32_e32 v80, v81, v80
	v_add_f32_e32 v179, v179, v80
	s_and_b64 vcc, exec, s[12:13]
	s_add_i32 s31, s31, 1
	s_mov_b32 s35, s27
	s_mov_b32 s27, s29
	s_mov_b32 s29, s34
	s_mov_b32 s34, s35
	s_add_i32 s12, s31, 3
	s_cmp_ge_i32 s12, s26
	s_cselect_b64 s[12:13], -1, 0
	s_add_i32 s14, s28, s31
	s_cbranch_vccnz .Lattn_tailbar
	s_waitcnt vmcnt(3) lgkmcnt(0)
	s_barrier
	s_cmp_eq_u32 s14, 0
	s_cbranch_scc0 .Lattn_top
	s_branch .LBB0_379
